# static s_setprio 1 for waves 0-3 (instead of 4-7) across the attention phases
# speedup vs baseline: 1.0065x; 1.0065x over previous
.LBB0_497:
	v_mov_b32_e32 v4, 0x5000
	global_load_dword v5, v4, s[80:81] sc1
	v_mov_b32_e32 v4, 0x23fd4
	s_waitcnt vmcnt(0)
	ds_write_b32 v4, v5
	s_waitcnt lgkmcnt(0)
	s_xor_b64 s[2:3], s[2:3], -1
	v_writelane_b32 v255, s2, 23
	s_nop 1
	v_writelane_b32 v255, s3, 24
	v_readlane_b32 s2, v254, 0
	s_cmp_le_i32 s2, s1
	s_cselect_b64 s[2:3], -1, 0
	s_cmp_lt_i32 s1, s84
	s_cselect_b64 s[4:5], -1, 0
	s_and_b64 s[2:3], s[2:3], s[4:5]
	s_andn2_b64 vcc, exec, s[2:3]
	s_cbranch_vccnz .LBB0_719
	v_readfirstlane_b32 s2, v210
	s_nop 3
	s_lshr_b32 s2, s2, 6
	s_cmp_lt_u32 s2, 4
	s_cbranch_scc0 .Lprio_att_done
	s_setprio 1
